# grid barrier: last XCD leader releases 16 per-XCD generation lines directly (fan-out) and every workgroup polls its own XCD line instead of one shared word
# speedup vs baseline: 1.0154x; 1.0005x over previous
; __device__ __forceinline__ unsigned xb_ld(unsigned* p)              { return __hip_atomic_load(p, __ATOMIC_RELAXED, __HIP_MEMORY_SCOPE_AGENT); }
; __device__ __forceinline__ unsigned xb_add(unsigned* p, unsigned v) { return __hip_atomic_fetch_add(p, v, __ATOMIC_RELAXED, __HIP_MEMORY_SCOPE_AGENT); }
; #define XB_SPIN(cond, bar) do { unsigned _sp = 0; while (cond) { __builtin_amdgcn_s_sleep(1); \
;     if ((++_sp & 255u) == 0u) { if (xb_ld(&(bar)[XB_TMO])) break; if (_sp > XB_SPIN_CAP) { atomicAdd(&(bar)[XB_TMO], 1u); break; } } } } while (0)
; __device__ __forceinline__ void xcd_barrier(const XcdBarrier& b) {
;     ...
;             const unsigned og = xb_add(&bar[XB_TOP], 1u);
;             const unsigned tg = og / nx;
;             if (og + 1u == (tg + 1u) * nx) xb_add(&bar[XB_TOPGEN], 1u);
;             else XB_SPIN(xb_ld(&bar[XB_TOPGEN]) == tg, bar);
.LBB0_98:
	s_or_b64 exec, exec, s[8:9]
	v_cvt_f32_u32_e32 v3, v0
	s_waitcnt vmcnt(0)
	v_readfirstlane_b32 s2, v2
	s_add_u32 s8, s72, 0x583500
	s_addc_u32 s9, s73, 0
	v_rcp_iflag_f32_e32 v3, v3
	v_add_u32_e32 v1, s2, v1
	v_add_u32_e32 v4, 1, v1
	s_mov_b64 s[10:11], -1
	v_mul_f32_e32 v2, 0x4f7ffffe, v3
	v_cvt_u32_f32_e32 v2, v2
	v_sub_u32_e32 v3, 0, v0
	v_mul_lo_u32 v3, v3, v2
	v_mul_hi_u32 v3, v2, v3
	v_add_u32_e32 v2, v2, v3
	v_mul_hi_u32 v2, v1, v2
	v_mul_lo_u32 v3, v2, v0
	v_sub_u32_e32 v1, v1, v3
	v_add_u32_e32 v5, 1, v2
	v_cmp_ge_u32_e32 vcc, v1, v0
	v_sub_u32_e32 v3, v1, v0
	s_nop 0
	v_cndmask_b32_e32 v2, v2, v5, vcc
	v_cndmask_b32_e32 v1, v1, v3, vcc
	v_add_u32_e32 v3, 1, v2
	v_cmp_ge_u32_e32 vcc, v1, v0
	s_nop 1
	v_cndmask_b32_e32 v2, v2, v3, vcc
	v_mul_lo_u32 v1, v0, v2
	v_add_u32_e32 v0, v1, v0
	v_cmp_ne_u32_e32 vcc, v4, v0
	v_mov_b64_e32 v[0:1], s[8:9]
	s_and_saveexec_b64 s[6:7], vcc
	s_cbranch_execz .LBB0_110
	v_mov_b32_e32 v0, 0
	v_mov_b32_e32 v3, 0x2000
	global_load_dword v1, v3, s[4:5] offset:1024 sc1
	s_mov_b64 s[14:15], 0
	s_waitcnt vmcnt(0)
	v_cmp_eq_u32_e32 vcc, v1, v2
	s_and_saveexec_b64 s[12:13], vcc
	s_cbranch_execz .LBB0_109
	s_add_u32 s10, s72, 0x580200
	s_addc_u32 s11, s73, 0
	s_mov_b32 s2, 1
	s_branch .LBB0_102

; __device__ __forceinline__ unsigned xb_ld(unsigned* p)              { return __hip_atomic_load(p, __ATOMIC_RELAXED, __HIP_MEMORY_SCOPE_AGENT); }
; #define XB_SPIN(cond, bar) do { unsigned _sp = 0; while (cond) { __builtin_amdgcn_s_sleep(1); \
;     if ((++_sp & 255u) == 0u) { if (xb_ld(&(bar)[XB_TMO])) break; if (_sp > XB_SPIN_CAP) { atomicAdd(&(bar)[XB_TMO], 1u); break; } } } } while (0)
; __device__ __forceinline__ void xcd_barrier(const XcdBarrier& b) {
;     ...
;             else XB_SPIN(xb_ld(&bar[XB_TOPGEN]) == tg, bar);
.LBB0_106:
	global_load_dword v1, v3, s[4:5] offset:1024 sc1
	s_add_i32 s2, s2, 1
	s_mov_b64 s[30:31], -1
	s_waitcnt vmcnt(0)
	v_cmp_ne_u32_e32 vcc, v1, v2
	s_orn2_b64 s[36:37], vcc, exec
	s_branch .LBB0_101

; __device__ __forceinline__ unsigned xb_add(unsigned* p, unsigned v) { return __hip_atomic_fetch_add(p, v, __ATOMIC_RELAXED, __HIP_MEMORY_SCOPE_AGENT); }
; __device__ __forceinline__ void xcd_barrier(const XcdBarrier& b) {
;     ...
;             if (og + 1u == (tg + 1u) * nx) xb_add(&bar[XB_TOPGEN], 1u);
.LBB0_110:
	s_or_b64 exec, exec, s[6:7]
	s_and_saveexec_b64 s[6:7], s[10:11]
	s_cbranch_execz .LBB0_112
	v_mov_b32_e32 v2, 1
	v_mov_b32_e32 v3, 0x582400
	global_atomic_add v3, v2, s[72:73]
	global_atomic_add v3, v2, s[72:73] offset:256
	global_atomic_add v3, v2, s[72:73] offset:512
	global_atomic_add v3, v2, s[72:73] offset:768
	global_atomic_add v3, v2, s[72:73] offset:1024
	global_atomic_add v3, v2, s[72:73] offset:1280
	global_atomic_add v3, v2, s[72:73] offset:1536
	global_atomic_add v3, v2, s[72:73] offset:1792
	global_atomic_add v3, v2, s[72:73] offset:2048
	global_atomic_add v3, v2, s[72:73] offset:2304
	global_atomic_add v3, v2, s[72:73] offset:2560
	global_atomic_add v3, v2, s[72:73] offset:2816
	global_atomic_add v3, v2, s[72:73] offset:3072
	global_atomic_add v3, v2, s[72:73] offset:3328
	global_atomic_add v3, v2, s[72:73] offset:3584
	global_atomic_add v3, v2, s[72:73] offset:3840
	global_atomic_add v[0:1], v2, off

; __device__ __forceinline__ unsigned xb_ld(unsigned* p)              { return __hip_atomic_load(p, __ATOMIC_RELAXED, __HIP_MEMORY_SCOPE_AGENT); }
; #define XB_SPIN(cond, bar) do { unsigned _sp = 0; while (cond) { __builtin_amdgcn_s_sleep(1); \
;     if ((++_sp & 255u) == 0u) { if (xb_ld(&(bar)[XB_TMO])) break; if (_sp > XB_SPIN_CAP) { atomicAdd(&(bar)[XB_TMO], 1u); break; } } } } while (0)
; __device__ __forceinline__ void xcd_barrier(const XcdBarrier& b) {
;     ...
;             else XB_SPIN(xb_ld(&bar[XB_TOPGEN]) == tg, bar);
.LBB0_339:
	global_load_dword v1, v3, s[4:5] offset:1024 sc1
	s_add_i32 s2, s2, 1
	s_mov_b64 s[18:19], -1
	s_waitcnt vmcnt(0)
	v_cmp_ne_u32_e32 vcc, v1, v2
	s_orn2_b64 s[24:25], vcc, exec
	s_branch .LBB0_334

; __device__ __forceinline__ unsigned xb_ld(unsigned* p)              { return __hip_atomic_load(p, __ATOMIC_RELAXED, __HIP_MEMORY_SCOPE_AGENT); }
; __device__ __forceinline__ unsigned xb_add(unsigned* p, unsigned v) { return __hip_atomic_fetch_add(p, v, __ATOMIC_RELAXED, __HIP_MEMORY_SCOPE_AGENT); }
; #define XB_SPIN(cond, bar) do { unsigned _sp = 0; while (cond) { __builtin_amdgcn_s_sleep(1); \
;     if ((++_sp & 255u) == 0u) { if (xb_ld(&(bar)[XB_TMO])) break; if (_sp > XB_SPIN_CAP) { atomicAdd(&(bar)[XB_TMO], 1u); break; } } } } while (0)
; __device__ __forceinline__ void xcd_barrier(const XcdBarrier& b) {
;     ...
;             const unsigned og = xb_add(&bar[XB_TOP], 1u);
;             const unsigned tg = og / nx;
;             if (og + 1u == (tg + 1u) * nx) xb_add(&bar[XB_TOPGEN], 1u);
;             else XB_SPIN(xb_ld(&bar[XB_TOPGEN]) == tg, bar);
.LBB0_430:
	s_or_b64 exec, exec, s[8:9]
	v_cvt_f32_u32_e32 v3, v0
	s_waitcnt vmcnt(0)
	v_readfirstlane_b32 s2, v2
	s_add_u32 s8, s72, 0x583500
	s_addc_u32 s9, s73, 0
	v_rcp_iflag_f32_e32 v3, v3
	v_add_u32_e32 v1, s2, v1
	v_add_u32_e32 v4, 1, v1
	s_mov_b64 s[10:11], -1
	v_mul_f32_e32 v2, 0x4f7ffffe, v3
	v_cvt_u32_f32_e32 v2, v2
	v_sub_u32_e32 v3, 0, v0
	v_mul_lo_u32 v3, v3, v2
	v_mul_hi_u32 v3, v2, v3
	v_add_u32_e32 v2, v2, v3
	v_mul_hi_u32 v2, v1, v2
	v_mul_lo_u32 v3, v2, v0
	v_sub_u32_e32 v1, v1, v3
	v_add_u32_e32 v5, 1, v2
	v_cmp_ge_u32_e32 vcc, v1, v0
	v_sub_u32_e32 v3, v1, v0
	s_nop 0
	v_cndmask_b32_e32 v2, v2, v5, vcc
	v_cndmask_b32_e32 v1, v1, v3, vcc
	v_add_u32_e32 v3, 1, v2
	v_cmp_ge_u32_e32 vcc, v1, v0
	s_nop 1
	v_cndmask_b32_e32 v2, v2, v3, vcc
	v_mul_lo_u32 v1, v0, v2
	v_add_u32_e32 v0, v1, v0
	v_cmp_ne_u32_e32 vcc, v4, v0
	v_mov_b64_e32 v[0:1], s[8:9]
	s_and_saveexec_b64 s[6:7], vcc
	s_cbranch_execz .LBB0_442
	v_mov_b32_e32 v0, 0
	v_mov_b32_e32 v3, 0x2000
	global_load_dword v1, v3, s[4:5] offset:1024 sc1
	s_mov_b64 s[16:17], 0
	s_waitcnt vmcnt(0)
	v_cmp_eq_u32_e32 vcc, v1, v2
	s_and_saveexec_b64 s[12:13], vcc
	s_cbranch_execz .LBB0_441
	s_add_u32 s10, s72, 0x580200
	s_addc_u32 s11, s73, 0
	s_mov_b32 s2, 1
	s_branch .LBB0_434

; __device__ __forceinline__ unsigned xb_ld(unsigned* p)              { return __hip_atomic_load(p, __ATOMIC_RELAXED, __HIP_MEMORY_SCOPE_AGENT); }
; #define XB_SPIN(cond, bar) do { unsigned _sp = 0; while (cond) { __builtin_amdgcn_s_sleep(1); \
;     if ((++_sp & 255u) == 0u) { if (xb_ld(&(bar)[XB_TMO])) break; if (_sp > XB_SPIN_CAP) { atomicAdd(&(bar)[XB_TMO], 1u); break; } } } } while (0)
; __device__ __forceinline__ void xcd_barrier(const XcdBarrier& b) {
;     ...
;             else XB_SPIN(xb_ld(&bar[XB_TOPGEN]) == tg, bar);
.LBB0_438:
	global_load_dword v1, v3, s[4:5] offset:1024 sc1
	s_add_i32 s2, s2, 1
	s_mov_b64 s[20:21], -1
	s_waitcnt vmcnt(0)
	v_cmp_ne_u32_e32 vcc, v1, v2
	s_orn2_b64 s[26:27], vcc, exec
	s_branch .LBB0_433

; __device__ __forceinline__ unsigned xb_ld(unsigned* p)              { return __hip_atomic_load(p, __ATOMIC_RELAXED, __HIP_MEMORY_SCOPE_AGENT); }
; #define XB_SPIN(cond, bar) do { unsigned _sp = 0; while (cond) { __builtin_amdgcn_s_sleep(1); \
;     if ((++_sp & 255u) == 0u) { if (xb_ld(&(bar)[XB_TMO])) break; if (_sp > XB_SPIN_CAP) { atomicAdd(&(bar)[XB_TMO], 1u); break; } } } } while (0)
; __device__ __forceinline__ void xcd_barrier(const XcdBarrier& b) {
;     ...
;             else XB_SPIN(xb_ld(&bar[XB_TOPGEN]) == tg, bar);
.LBB0_598:
	global_load_dword v1, v3, s[4:5] offset:1024 sc1
	s_add_i32 s2, s2, 1
	s_mov_b64 s[18:19], -1
	s_waitcnt vmcnt(0)
	v_cmp_ne_u32_e32 vcc, v1, v2
	s_orn2_b64 s[22:23], vcc, exec
	s_branch .LBB0_593

; __device__ __forceinline__ unsigned xb_ld(unsigned* p)              { return __hip_atomic_load(p, __ATOMIC_RELAXED, __HIP_MEMORY_SCOPE_AGENT); }
; __device__ __forceinline__ unsigned xb_add(unsigned* p, unsigned v) { return __hip_atomic_fetch_add(p, v, __ATOMIC_RELAXED, __HIP_MEMORY_SCOPE_AGENT); }
; #define XB_SPIN(cond, bar) do { unsigned _sp = 0; while (cond) { __builtin_amdgcn_s_sleep(1); \
;     if ((++_sp & 255u) == 0u) { if (xb_ld(&(bar)[XB_TMO])) break; if (_sp > XB_SPIN_CAP) { atomicAdd(&(bar)[XB_TMO], 1u); break; } } } } while (0)
; __device__ __forceinline__ void xcd_barrier(const XcdBarrier& b) {
;     ...
;             const unsigned og = xb_add(&bar[XB_TOP], 1u);
;             const unsigned tg = og / nx;
;             if (og + 1u == (tg + 1u) * nx) xb_add(&bar[XB_TOPGEN], 1u);
;             else XB_SPIN(xb_ld(&bar[XB_TOPGEN]) == tg, bar);
.LBB0_1097:
	s_or_b64 exec, exec, s[10:11]
	v_cvt_f32_u32_e32 v3, v0
	s_waitcnt vmcnt(0)
	v_readfirstlane_b32 s2, v2
	s_add_u32 s10, s72, 0x583500
	s_addc_u32 s11, s73, 0
	v_rcp_iflag_f32_e32 v3, v3
	v_add_u32_e32 v1, s2, v1
	v_add_u32_e32 v4, 1, v1
	s_mov_b64 s[12:13], -1
	v_mul_f32_e32 v2, 0x4f7ffffe, v3
	v_cvt_u32_f32_e32 v2, v2
	v_sub_u32_e32 v3, 0, v0
	v_mul_lo_u32 v3, v3, v2
	v_mul_hi_u32 v3, v2, v3
	v_add_u32_e32 v2, v2, v3
	v_mul_hi_u32 v2, v1, v2
	v_mul_lo_u32 v3, v2, v0
	v_sub_u32_e32 v1, v1, v3
	v_add_u32_e32 v5, 1, v2
	v_cmp_ge_u32_e32 vcc, v1, v0
	v_sub_u32_e32 v3, v1, v0
	s_nop 0
	v_cndmask_b32_e32 v2, v2, v5, vcc
	v_cndmask_b32_e32 v1, v1, v3, vcc
	v_add_u32_e32 v3, 1, v2
	v_cmp_ge_u32_e32 vcc, v1, v0
	s_nop 1
	v_cndmask_b32_e32 v2, v2, v3, vcc
	v_mul_lo_u32 v1, v0, v2
	v_add_u32_e32 v0, v1, v0
	v_cmp_ne_u32_e32 vcc, v4, v0
	v_mov_b64_e32 v[0:1], s[10:11]
	s_and_saveexec_b64 s[8:9], vcc
	s_cbranch_execz .LBB0_1109
	v_mov_b32_e32 v0, 0
	v_mov_b32_e32 v3, 0x2000
	global_load_dword v1, v3, s[6:7] offset:1024 sc1
	s_mov_b64 s[16:17], 0
	s_waitcnt vmcnt(0)
	v_cmp_eq_u32_e32 vcc, v1, v2
	s_and_saveexec_b64 s[14:15], vcc
	s_cbranch_execz .LBB0_1108
	s_add_u32 s12, s72, 0x580200
	s_addc_u32 s13, s73, 0
	s_mov_b32 s2, 1
	s_branch .LBB0_1101

; __device__ __forceinline__ unsigned xb_ld(unsigned* p)              { return __hip_atomic_load(p, __ATOMIC_RELAXED, __HIP_MEMORY_SCOPE_AGENT); }
; #define XB_SPIN(cond, bar) do { unsigned _sp = 0; while (cond) { __builtin_amdgcn_s_sleep(1); \
;     if ((++_sp & 255u) == 0u) { if (xb_ld(&(bar)[XB_TMO])) break; if (_sp > XB_SPIN_CAP) { atomicAdd(&(bar)[XB_TMO], 1u); break; } } } } while (0)
; __device__ __forceinline__ void xcd_barrier(const XcdBarrier& b) {
;     ...
;             else XB_SPIN(xb_ld(&bar[XB_TOPGEN]) == tg, bar);
.LBB0_1105:
	global_load_dword v1, v3, s[6:7] offset:1024 sc1
	s_add_i32 s2, s2, 1
	s_mov_b64 s[20:21], -1
	s_waitcnt vmcnt(0)
	v_cmp_ne_u32_e32 vcc, v1, v2
	s_orn2_b64 s[24:25], vcc, exec
	s_branch .LBB0_1100

; __device__ __forceinline__ unsigned xb_add(unsigned* p, unsigned v) { return __hip_atomic_fetch_add(p, v, __ATOMIC_RELAXED, __HIP_MEMORY_SCOPE_AGENT); }
; __device__ __forceinline__ void xcd_barrier(const XcdBarrier& b) {
;     ...
;             if (og + 1u == (tg + 1u) * nx) xb_add(&bar[XB_TOPGEN], 1u);
.LBB0_1109:
	s_or_b64 exec, exec, s[8:9]
	s_and_saveexec_b64 s[8:9], s[12:13]
	s_cbranch_execz .LBB0_1111
	v_mov_b32_e32 v2, 1
	v_mov_b32_e32 v3, 0x582400
	global_atomic_add v3, v2, s[72:73]
	global_atomic_add v3, v2, s[72:73] offset:256
	global_atomic_add v3, v2, s[72:73] offset:512
	global_atomic_add v3, v2, s[72:73] offset:768
	global_atomic_add v3, v2, s[72:73] offset:1024
	global_atomic_add v3, v2, s[72:73] offset:1280
	global_atomic_add v3, v2, s[72:73] offset:1536
	global_atomic_add v3, v2, s[72:73] offset:1792
	global_atomic_add v3, v2, s[72:73] offset:2048
	global_atomic_add v3, v2, s[72:73] offset:2304
	global_atomic_add v3, v2, s[72:73] offset:2560
	global_atomic_add v3, v2, s[72:73] offset:2816
	global_atomic_add v3, v2, s[72:73] offset:3072
	global_atomic_add v3, v2, s[72:73] offset:3328
	global_atomic_add v3, v2, s[72:73] offset:3584
	global_atomic_add v3, v2, s[72:73] offset:3840
	global_atomic_add v[0:1], v2, off

; __device__ __forceinline__ unsigned xb_ld(unsigned* p)              { return __hip_atomic_load(p, __ATOMIC_RELAXED, __HIP_MEMORY_SCOPE_AGENT); }
; __device__ __forceinline__ unsigned xb_add(unsigned* p, unsigned v) { return __hip_atomic_fetch_add(p, v, __ATOMIC_RELAXED, __HIP_MEMORY_SCOPE_AGENT); }
; #define XB_SPIN(cond, bar) do { unsigned _sp = 0; while (cond) { __builtin_amdgcn_s_sleep(1); \
;     if ((++_sp & 255u) == 0u) { if (xb_ld(&(bar)[XB_TMO])) break; if (_sp > XB_SPIN_CAP) { atomicAdd(&(bar)[XB_TMO], 1u); break; } } } } while (0)
; __device__ __forceinline__ void xcd_barrier(const XcdBarrier& b) {
;     ...
;             const unsigned og = xb_add(&bar[XB_TOP], 1u);
;             const unsigned tg = og / nx;
;             if (og + 1u == (tg + 1u) * nx) xb_add(&bar[XB_TOPGEN], 1u);
;             else XB_SPIN(xb_ld(&bar[XB_TOPGEN]) == tg, bar);
.LBB0_1288:
	s_or_b64 exec, exec, s[8:9]
	v_cvt_f32_u32_e32 v3, v0
	s_waitcnt vmcnt(0)
	v_readfirstlane_b32 s2, v2
	s_add_u32 s8, s72, 0x583500
	s_addc_u32 s9, s73, 0
	v_rcp_iflag_f32_e32 v3, v3
	v_add_u32_e32 v1, s2, v1
	v_add_u32_e32 v4, 1, v1
	s_mov_b64 s[10:11], -1
	v_mul_f32_e32 v2, 0x4f7ffffe, v3
	v_cvt_u32_f32_e32 v2, v2
	v_sub_u32_e32 v3, 0, v0
	v_mul_lo_u32 v3, v3, v2
	v_mul_hi_u32 v3, v2, v3
	v_add_u32_e32 v2, v2, v3
	v_mul_hi_u32 v2, v1, v2
	v_mul_lo_u32 v3, v2, v0
	v_sub_u32_e32 v1, v1, v3
	v_add_u32_e32 v5, 1, v2
	v_cmp_ge_u32_e32 vcc, v1, v0
	v_sub_u32_e32 v3, v1, v0
	s_nop 0
	v_cndmask_b32_e32 v2, v2, v5, vcc
	v_cndmask_b32_e32 v1, v1, v3, vcc
	v_add_u32_e32 v3, 1, v2
	v_cmp_ge_u32_e32 vcc, v1, v0
	s_nop 1
	v_cndmask_b32_e32 v2, v2, v3, vcc
	v_mul_lo_u32 v1, v0, v2
	v_add_u32_e32 v0, v1, v0
	v_cmp_ne_u32_e32 vcc, v4, v0
	v_mov_b64_e32 v[0:1], s[8:9]
	s_and_saveexec_b64 s[6:7], vcc
	s_cbranch_execz .LBB0_1300
	v_mov_b32_e32 v0, 0
	v_mov_b32_e32 v3, 0x2000
	global_load_dword v1, v3, s[4:5] offset:1024 sc1
	s_mov_b64 s[16:17], 0
	s_waitcnt vmcnt(0)
	v_cmp_eq_u32_e32 vcc, v1, v2
	s_and_saveexec_b64 s[14:15], vcc
	s_cbranch_execz .LBB0_1299
	s_add_u32 s10, s72, 0x580200
	s_addc_u32 s11, s73, 0
	s_mov_b32 s2, 1
	s_branch .LBB0_1292

; __device__ __forceinline__ unsigned xb_ld(unsigned* p)              { return __hip_atomic_load(p, __ATOMIC_RELAXED, __HIP_MEMORY_SCOPE_AGENT); }
; #define XB_SPIN(cond, bar) do { unsigned _sp = 0; while (cond) { __builtin_amdgcn_s_sleep(1); \
;     if ((++_sp & 255u) == 0u) { if (xb_ld(&(bar)[XB_TMO])) break; if (_sp > XB_SPIN_CAP) { atomicAdd(&(bar)[XB_TMO], 1u); break; } } } } while (0)
; __device__ __forceinline__ void xcd_barrier(const XcdBarrier& b) {
;     ...
;             else XB_SPIN(xb_ld(&bar[XB_TOPGEN]) == tg, bar);
.LBB0_1296:
	global_load_dword v1, v3, s[4:5] offset:1024 sc1
	s_add_i32 s2, s2, 1
	s_mov_b64 s[20:21], -1
	s_waitcnt vmcnt(0)
	v_cmp_ne_u32_e32 vcc, v1, v2
	s_orn2_b64 s[24:25], vcc, exec
	s_branch .LBB0_1291
